# grid barrier: the XCD's last arriver also invalidates that L2 once (all its blocks are idle in the barrier from then until the release), members invalidate only their L1 after the release
# speedup vs baseline: 1.0062x; 1.0062x over previous
; DI void grid_barrier(unsigned* ctr, unsigned target) {
;   __syncthreads();
;   if (threadIdx.x == 0) {
;     __threadfence();
;     __hip_atomic_fetch_add(ctr, 1u, __ATOMIC_RELAXED, __HIP_MEMORY_SCOPE_AGENT);
;     unsigned spins = 0;
;     while (__hip_atomic_load(ctr, __ATOMIC_RELAXED, __HIP_MEMORY_SCOPE_AGENT) < target && spins < (1u << 26)) { __builtin_amdgcn_s_sleep(2); ++spins; }
;     __threadfence();
;   }
;   __syncthreads();
; }
.Lg3_real:
	v_readlane_b32 s10, v252, 10
	v_readlane_b32 s11, v252, 11
	s_sub_u32 s14, s33, s10
	s_add_u32 s14, s14, 7
	s_lshr_b32 s14, s14, 3
	s_sub_u32 s15, s4, 1
	s_mul_i32 s11, s11, s15
	s_add_u32 s11, s11, s14
	s_lshl_b32 s10, s10, 7
	s_add_u32 s22, s24, s10
	s_addc_u32 s23, s25, 0
	global_atomic_add v1, v131, v0, s[22:23] offset:256 sc0
	s_waitcnt vmcnt(0)
	v_add_u32_e32 v1, 1, v1
	v_cmp_eq_u32_e32 vcc, s11, v1
	s_mov_b32 s10, 0
	s_cbranch_vccz .Lg3_nl
	buffer_wbl2 sc1
	s_waitcnt vmcnt(0)
	buffer_inv sc1
	s_waitcnt vmcnt(0)
	global_atomic_add v131, v0, s[24:25] offset:-1792
	global_atomic_add v131, v0, s[24:25] offset:-1664
	global_atomic_add v131, v0, s[24:25] offset:-1536
	global_atomic_add v131, v0, s[24:25] offset:-1408
	global_atomic_add v131, v0, s[24:25] offset:-1280
	global_atomic_add v131, v0, s[24:25] offset:-1152
	global_atomic_add v131, v0, s[24:25] offset:-1024
	global_atomic_add v131, v0, s[24:25] offset:-896
	s_branch .Lg3_w2
.Lg3_nl:
.Lg3_w2:
	v_readlane_b32 s11, v252, 12
	s_min_u32 s14, s33, 8
	s_mul_i32 s11, s11, s15
	s_add_u32 s11, s11, s14

; DI void grid_barrier(unsigned* ctr, unsigned target) {
;   __syncthreads();
;   if (threadIdx.x == 0) {
;     __threadfence();
;     __hip_atomic_fetch_add(ctr, 1u, __ATOMIC_RELAXED, __HIP_MEMORY_SCOPE_AGENT);
;     unsigned spins = 0;
;     while (__hip_atomic_load(ctr, __ATOMIC_RELAXED, __HIP_MEMORY_SCOPE_AGENT) < target && spins < (1u << 26)) { __builtin_amdgcn_s_sleep(2); ++spins; }
;     __threadfence();
;   }
;   __syncthreads();
; }
.Lg3_okb:
	buffer_inv sc0
	s_branch .Lg3_fin

; DI void grid_barrier(unsigned* ctr, unsigned target) {
;   __syncthreads();
;   if (threadIdx.x == 0) {
;     __threadfence();
;     __hip_atomic_fetch_add(ctr, 1u, __ATOMIC_RELAXED, __HIP_MEMORY_SCOPE_AGENT);
;     unsigned spins = 0;
;     while (__hip_atomic_load(ctr, __ATOMIC_RELAXED, __HIP_MEMORY_SCOPE_AGENT) < target && spins < (1u << 26)) { __builtin_amdgcn_s_sleep(2); ++spins; }
;     __threadfence();
;   }
;   __syncthreads();
; }
.Lg3_fin:
.LBB0_879:
	s_or_b64 exec, exec, s[8:9]
	s_mov_b64 s[10:11], -1
	s_barrier
